# as v163 plus grid-barrier non-leaders invalidate only their L1 (buffer_inv sc0; the XCD's last arriver still does the agent-scope invalidate after all local workgroups arrived) and the same-XCD panel
# speedup vs baseline: 1.0095x; 1.0011x over previous
.LBB0_187:
	s_lshl_b32 s4, s33, 8
	s_add_u32 s25, s2, s4
	s_addc_u32 s24, s3, 0
	v_mov_b32_e32 v1, s25
	v_add_co_u32_e32 v4, vcc, 0x1000, v1
	v_mov_b32_e32 v1, s24
	s_nop 0
	v_addc_co_u32_e32 v5, vcc, 0, v1, vcc
	v_mov_b32_e32 v1, 1
	flat_atomic_add v1, v[4:5], v1 offset:1024 sc0
	v_cvt_f32_u32_e32 v3, v2
	v_sub_u32_e32 v4, 0, v2
	v_rcp_iflag_f32_e32 v3, v3
	s_nop 0
	v_mul_f32_e32 v3, 0x4f7ffffe, v3
	v_cvt_u32_f32_e32 v3, v3
	v_mul_lo_u32 v4, v4, v3
	v_mul_hi_u32 v4, v3, v4
	v_add_u32_e32 v3, v3, v4
	s_waitcnt vmcnt(0) lgkmcnt(0)
	v_mul_hi_u32 v3, v1, v3
	v_mul_lo_u32 v5, v3, v2
	v_add_u32_e32 v4, 1, v1
	v_sub_u32_e32 v1, v1, v5
	v_add_u32_e32 v6, 1, v3
	v_cmp_ge_u32_e32 vcc, v1, v2
	v_sub_u32_e32 v5, v1, v2
	s_nop 0
	v_cndmask_b32_e32 v3, v3, v6, vcc
	v_cndmask_b32_e32 v1, v1, v5, vcc
	v_add_u32_e32 v5, 1, v3
	v_cmp_ge_u32_e32 vcc, v1, v2
	s_nop 1
	v_cndmask_b32_e32 v1, v3, v5, vcc
	v_mad_u64_u32 v[2:3], s[4:5], v2, v1, v[2:3]
	v_cmp_ne_u32_e32 vcc, v4, v2
	s_and_saveexec_b64 s[4:5], vcc
	s_xor_b64 s[4:5], exec, s[4:5]
	s_cbranch_execz .LBB0_200
	v_mov_b32_e32 v0, s25
	v_add_co_u32_e32 v2, vcc, 0x2000, v0
	v_mov_b32_e32 v0, s24
	s_nop 0
	v_addc_co_u32_e32 v3, vcc, 0, v0, vcc
	buffer_inv sc0
	flat_load_dword v0, v[2:3] offset:1024 sc1
	s_add_u32 s8, s25, 0x2400
	s_addc_u32 s9, s24, 0
	s_waitcnt vmcnt(0) lgkmcnt(0)
	v_cmp_eq_u32_e32 vcc, v0, v1
	s_and_saveexec_b64 s[6:7], vcc
	s_cbranch_execz .LBB0_199
	s_mov_b32 s26, 1
	s_mov_b64 s[10:11], 0
	s_branch .LBB0_191

.LBB0_437:
	s_lshl_b32 s4, s38, 8
	s_add_u32 s25, s2, s4
	s_addc_u32 s24, s3, 0
	v_mov_b32_e32 v1, s25
	v_add_co_u32_e32 v4, vcc, 0x1000, v1
	v_mov_b32_e32 v1, s24
	s_nop 0
	v_addc_co_u32_e32 v5, vcc, 0, v1, vcc
	flat_atomic_add v3, v[4:5], v176 offset:1024 sc0
	v_cvt_f32_u32_e32 v1, v2
	v_sub_u32_e32 v4, 0, v2
	v_rcp_iflag_f32_e32 v1, v1
	s_nop 0
	v_mul_f32_e32 v1, 0x4f7ffffe, v1
	v_cvt_u32_f32_e32 v1, v1
	v_mul_lo_u32 v4, v4, v1
	v_mul_hi_u32 v4, v1, v4
	v_add_u32_e32 v1, v1, v4
	s_waitcnt vmcnt(0) lgkmcnt(0)
	v_mul_hi_u32 v1, v3, v1
	v_mul_lo_u32 v4, v1, v2
	v_sub_u32_e32 v4, v3, v4
	v_cmp_ge_u32_e32 vcc, v4, v2
	v_add_u32_e32 v5, 1, v1
	s_nop 0
	v_cndmask_b32_e32 v1, v1, v5, vcc
	v_sub_u32_e32 v5, v4, v2
	v_cndmask_b32_e32 v4, v4, v5, vcc
	v_cmp_ge_u32_e32 vcc, v4, v2
	v_add_u32_e32 v4, 1, v1
	s_nop 0
	v_cndmask_b32_e32 v1, v1, v4, vcc
	v_add_u32_e32 v4, 1, v3
	v_mad_u64_u32 v[2:3], s[4:5], v2, v1, v[2:3]
	v_cmp_ne_u32_e32 vcc, v4, v2
	s_and_saveexec_b64 s[4:5], vcc
	s_xor_b64 s[4:5], exec, s[4:5]
	s_cbranch_execz .LBB0_450
	v_mov_b32_e32 v0, s25
	v_add_co_u32_e32 v2, vcc, 0x2000, v0
	v_mov_b32_e32 v0, s24
	s_nop 0
	v_addc_co_u32_e32 v3, vcc, 0, v0, vcc
	buffer_inv sc0
	flat_load_dword v0, v[2:3] offset:1024 sc1
	s_add_u32 s8, s25, 0x2400
	s_addc_u32 s9, s24, 0
	s_waitcnt vmcnt(0) lgkmcnt(0)
	v_cmp_eq_u32_e32 vcc, v0, v1
	s_and_saveexec_b64 s[6:7], vcc
	s_cbranch_execz .LBB0_449
	s_mov_b32 s26, 1
	s_mov_b64 s[10:11], 0
	s_branch .LBB0_441

.Lmy_pw1_ok:
	s_getreg_b32 m0, hwreg(HW_REG_XCC_ID, 0, 4)
	s_bfe_u32 vcc_hi, vcc_lo, 0x80008
	s_lshr_b32 vcc_lo, vcc_lo, 16
	s_mul_i32 vcc_hi, vcc_hi, m0
	s_lshl_b32 vcc_hi, vcc_hi, 1
	s_mul_i32 m0, m0, m0
	s_lshl_b32 m0, m0, 3
	s_add_u32 vcc_lo, vcc_lo, m0
	s_cmp_eq_u32 vcc_lo, vcc_hi
	s_cbranch_scc1 .Lmy_pw1_l1
	buffer_inv sc1
	s_branch .Lmy_pw1_w
.Lmy_pw1_l1:
	buffer_inv sc0

.LBB0_949:
	s_or_b64 exec, exec, s[4:5]
	s_mov_b64 s[4:5], s[74:75]
	s_getreg_b32 s2, hwreg(HW_REG_HW_ID, 0, 6)
	s_lshl_b32 s2, s2, 2
	s_and_b32 s2, s2, 0xfc
	s_add_i32 s2, s2, 0
	s_add_i32 s2, s2, 0x20200
	v_mov_b32_e32 v0, s2
	ds_read_b32 v0, v0
	v_mbcnt_lo_u32_b32 v1, -1, 0
	v_mbcnt_hi_u32_b32 v1, -1, v1
	s_waitcnt lgkmcnt(0)
	v_readfirstlane_b32 s2, v0
	s_lshl_b32 s2, s2, 6
	v_sub_u32_e32 v0, 0, v1
	v_cmp_eq_u32_e32 vcc, s2, v0
	s_and_saveexec_b64 s[2:3], vcc
	s_branch .LBB0_962
	s_nop 0
	s_nop 0
	s_nop 0
	s_nop 0
	s_nop 0
	s_nop 0
	s_nop 0
.LBB0_962:
	s_or_b64 exec, exec, s[2:3]
	s_mov_b64 s[2:3], s[74:75]
	s_mov_b64 s[8:9], s[74:75]
	s_mov_b64 s[0:1], s[74:75]
	s_mov_b64 s[12:13], s[74:75]
	s_barrier
	s_getreg_b32 s4, hwreg(HW_REG_HW_ID, 0, 6)
	s_lshl_b32 s4, s4, 2
	s_and_b32 s4, s4, 0xfc
	s_add_i32 s4, s4, 0
	s_add_i32 s4, s4, 0x20200
	v_mov_b32_e32 v0, s4
	ds_read_b32 v0, v0
	v_mbcnt_lo_u32_b32 v56, -1, 0
	v_mbcnt_hi_u32_b32 v56, -1, v56
	s_and_b64 vcc, exec, s[6:7]
	s_waitcnt lgkmcnt(0)
	v_readfirstlane_b32 s4, v0
	s_nop 1
	v_lshl_add_u32 v30, s4, 6, v56
	s_nop 0
	v_readfirstlane_b32 s17, v30
	s_cbranch_vccnz .LBB0_1074
	s_load_dwordx2 s[4:5], s[2:3], 0xf8
	s_nop 0
	s_load_dwordx2 s[2:3], s[8:9], 0xf8
	s_nop 0
	s_load_dwordx4 s[8:11], s[12:13], 0xf0
	s_getreg_b32 s6, hwreg(HW_REG_HW_ID, 0, 6)
	s_lshl_b32 s6, s6, 2
	s_and_b32 s6, s6, 0xfc
	s_add_i32 s6, s6, 0
	s_add_i32 s6, s6, 0x20200
	v_mov_b32_e32 v0, s6
	s_ashr_i32 s20, s17, 8
	ds_read_b32 v0, v0
	s_lshl_b32 s16, s20, 6
	v_readlane_b32 s12, v253, 61
	v_mbcnt_lo_u32_b32 v4, -1, 0
	v_mbcnt_hi_u32_b32 v4, -1, v4
	v_readlane_b32 s6, v253, 9
	s_waitcnt lgkmcnt(0)
	v_and_or_b32 v0, v4, 15, s16
	v_readlane_b32 s13, v253, 62
	v_add_u32_e32 v24, s6, v0
	s_mov_b64 s[6:7], -1
	s_and_b64 vcc, exec, s[12:13]
	s_cbranch_vccz .LBB0_965
	v_ashrrev_i32_e32 v25, 31, v24
	s_mov_b64 s[6:7], 0
	v_mov_b64_e32 v[0:1], v[24:25]

.Lmy_pw2_w:
	s_waitcnt vmcnt(0)
.Lmy_pw2_done:
	s_barrier
